# FoX unit prologue: gain_max over 64 gains as one lane-parallel load + wave max instead of 32 serialized load/wait round trips
# speedup vs baseline: 1.0071x; 1.0071x over previous
.LBB0_1677:
	s_or_b64 exec, exec, s[0:1]
	s_mov_b32 s0, s33
	s_barrier
	s_ashr_i32 s8, s91, 2
	v_mov_b32_e32 v0, s0
	ds_read2_b32 v[2:3], v0 offset1:1
	s_and_b32 s22, s91, 3
	v_mov_b32_e32 v115, v1
	s_mov_b32 s24, -2
	s_mov_b64 s[20:21], 0
	s_waitcnt lgkmcnt(0)
	v_readfirstlane_b32 s0, v2
	s_add_u32 s10, s0, 0xaa00000
	s_mov_b32 s0, s33
	v_readfirstlane_b32 s1, v3
	v_mov_b32_e32 v0, s0
	ds_read2_b32 v[2:3], v0 offset1:1
	s_addc_u32 s11, s1, 0
	v_mov_b32_e32 v5, 0
	s_waitcnt lgkmcnt(0)
	v_readfirstlane_b32 s0, v2
	s_add_u32 s2, s0, 0x10300000
	s_mov_b32 s0, s33
	v_readfirstlane_b32 s1, v3
	v_mov_b32_e32 v0, s0
	ds_read2_b32 v[2:3], v0 offset1:1
	v_readlane_b32 s0, v254, 24
	s_addc_u32 s3, s1, 0
	s_waitcnt lgkmcnt(0)
	v_readfirstlane_b32 s6, v2
	v_mov_b32_e32 v0, s0
	v_readfirstlane_b32 s7, v3
	ds_read2_b32 v[2:3], v0 offset1:1
	v_readlane_b32 s0, v254, 57
	v_readlane_b32 s1, v254, 58
	s_lshl_b64 s[0:1], s[0:1], 2
	v_mov_b32_e32 v0, v1
	s_waitcnt lgkmcnt(0)
	v_readfirstlane_b32 s9, v2
	v_readfirstlane_b32 s12, v3
	s_add_u32 s14, s9, s0
	s_getreg_b32 s0, hwreg(HW_REG_HW_ID, 0, 6)
	s_addc_u32 s15, s12, s1
	s_lshl_b32 s0, s0, 2
	s_and_b32 s0, s0, 0xfc
	v_add_u32_e32 v2, s0, v0
	v_add_u32_e32 v2, 0x24800, v2
	ds_read_b32 v2, v2
	v_mbcnt_lo_u32_b32 v0, -1, v0
	v_mbcnt_hi_u32_b32 v13, -1, v0
	s_lshl_b32 s23, s86, 8
	v_and_b32_e32 v14, 31, v13
	s_waitcnt lgkmcnt(0)
	v_readfirstlane_b32 s0, v2
	s_ashr_i32 s9, s8, 31
	s_lshl_b64 s[12:13], s[8:9], 13
	v_lshl_add_u32 v110, s0, 6, v13
	v_ashrrev_i32_e32 v0, 6, v110
	v_lshl_add_u32 v120, v0, 5, s23
	v_or_b32_e32 v112, v120, v14
	v_ashrrev_i32_e32 v113, 31, v112
	v_lshl_add_u64 v[108:109], s[12:13], 0, v[112:113]
	v_mov_b64_e32 v[2:3], s[10:11]
	v_mad_u64_u32 v[2:3], s[0:1], v108, s89, v[2:3]
	v_bfe_u32 v15, v13, 5, 1
	v_mad_i32_i24 v3, v109, s89, v3
	s_lshl_b32 s94, s22, 7
	v_lshl_add_u64 v[2:3], v[2:3], 0, s[94:95]
	v_lshlrev_b32_e32 v114, 4, v15
	v_lshl_add_u64 v[2:3], v[2:3], 0, v[114:115]
	global_load_dwordx4 v[80:83], v[2:3], off offset:1536
	global_load_dwordx4 v[84:87], v[2:3], off offset:1568
	global_load_dwordx4 v[88:91], v[2:3], off offset:1600
	global_load_dwordx4 v[92:95], v[2:3], off offset:1632
	v_lshl_add_u64 v[2:3], v[108:109], 4, s[2:3]
	s_lshl_b32 s94, s22, 2
	v_lshl_add_u64 v[2:3], v[2:3], 0, s[94:95]
	global_load_dword v2, v[2:3], off
	v_and_b32_e32 v12, 63, v13
	s_lshl_b32 s9, s22, 6
	v_mov_b32_e32 v3, 0
	s_mov_b64 s[18:19], s[14:15]
	v_lshlrev_b32_e32 v4, 2, v13
	global_load_dword v4, v4, s[14:15]
	s_waitcnt vmcnt(0)
	v_max_f32_e64 v3, |v4|, |v4|
	v_mov_b32_e32 v4, v3
	s_nop 1
	v_permlane32_swap_b32_e32 v4, v3
	v_max_f32_e32 v3, v3, v4
	v_mov_b32_e32 v4, v3
	s_nop 1
	v_permlane16_swap_b32_e32 v4, v3
	v_max_f32_e32 v3, v3, v4
	s_nop 1
	v_max_f32_dpp v3, v3, v3 row_ror:8 row_mask:0xf bank_mask:0xf
	s_nop 1
	v_max_f32_dpp v3, v3, v3 row_ror:4 row_mask:0xf bank_mask:0xf
	s_nop 1
	v_max_f32_dpp v3, v3, v3 row_ror:2 row_mask:0xf bank_mask:0xf
	s_nop 1
	v_max_f32_dpp v3, v3, v3 row_ror:1 row_mask:0xf bank_mask:0xf
	s_nop 1
